# in-projection column-tile rotation (4 activation tiles per block) on top of the widened FFN-down residual loads, placement kept (+128 B)
# speedup vs baseline: 1.0035x; 1.0018x over previous
.LBB0_64:
	s_add_u32 s62, s68, 0x3200000
	s_addc_u32 s63, s69, 0
	s_add_u32 s88, s68, 0x7200000
	s_addc_u32 s89, s69, 0
	s_cmp_lt_i32 s70, 2
	s_cselect_b64 s[0:1], -1, 0
	s_cmp_gt_i32 s71, 1
	s_cselect_b64 s[2:3], -1, 0
	s_and_b64 s[0:1], s[0:1], s[2:3]
	s_andn2_b64 vcc, exec, s[0:1]
	s_cbranch_vccnz .LBB0_174
	s_cmpk_lt_i32 s93, 0x800
	s_cselect_b64 s[0:1], -1, 0
	s_cmpk_gt_i32 s93, 0x7ff
	v_readfirstlane_b32 s10, v186
	s_cbranch_scc1 .LBB0_71
	s_ashr_i32 s2, s93, 31
	s_lshr_b32 s2, s2, 29
	s_add_i32 s4, s93, s2
	s_and_b32 s2, s4, -8
	s_sub_i32 s5, s93, s2
	s_cmp_gt_i32 s5, -1
	s_cbranch_scc0 .LBB0_68
	s_lshl_b32 s6, s5, 8
	s_cbranch_execz .LBB0_69
	s_branch .LBB0_70
	s_nop 0
	s_nop 0
	s_nop 0
	s_nop 0
	s_nop 0
	s_nop 0
	s_nop 0
	s_nop 0
	s_nop 0
	s_nop 0
	s_nop 0
	s_nop 0
	s_nop 0
	s_nop 0
	s_nop 0
	s_nop 0
	s_nop 0
	s_nop 0
	s_nop 0
	s_nop 0
	s_nop 0
	s_nop 0
